# P3: workgroups on odd XCDs run the GLA intra-chunk units before the projection GEMMs (even ones after) to overlap memory-bound and MFMA-bound work
# baseline (speedup 1.0000x reference)
; __global__ void __launch_bounds__(NTHREADS, 2) hybrid_block_fwd(Params P) {
;     ...
;     if (PH(4)) { pg8::Gemm g{(const bf16_t*)(ws + WS_CQN), (const bf16_t*)(ws + WS_WUQ), M, QC, 512, 512, 512}; pg8::StaticOrder S; S.init(M, QC, G, bx);
;       pg8::EpiRowScaleRope E{(bf16_t*)(ws + WS_Q), QC, QSCALE, 4, (const float*)(ws + WS_CS)};
;       pg8::gemm_phase<pg8::EpiRowScaleRope, pg8::StaticOrder, P3_ALIGN, P3_SP2>(lds, g, S, E); }
;     ...
;     if (PH(7)) for (int rep = 0; rep < REP_GLA; ++rep) for (int u = bx; u < 1024; u += G) gla_intra_unit(P, lds, u);
.LBB0_354:
	s_or_b64 exec, exec, s[0:1]
	v_mov_b32_e32 v12, v168
	s_cmpk_lt_i32 s2, 0x180
	s_waitcnt lgkmcnt(0)
	s_barrier
	s_mov_b32 s98, 0
	s_cmpk_lg_u32 s92, 0x100
	s_cbranch_scc1 .Lp3_gemm_pre
	s_bitcmp1_b32 s2, 0
	s_cbranch_scc0 .Lp3_gemm_pre
	s_mov_b32 s98, 1
	s_mov_b64 s[100:101], s[28:29]
	s_branch .LBB0_421
.Lp3_gemm_pre:
	s_cmpk_lt_i32 s2, 0x180
.Lp3_gemm_entry:
	s_cselect_b64 s[0:1], -1, 0
	s_cmpk_gt_i32 s2, 0x17f
	v_readfirstlane_b32 s4, v12
	s_cbranch_scc1 .LBB0_356
	s_ashr_i32 s3, s2, 31
	s_lshr_b32 s3, s3, 29
	s_add_i32 s3, s2, s3
	s_ashr_i32 s22, s3, 3
	s_and_b32 s3, s3, -8
	s_sub_i32 s3, s2, s3
	s_cmp_lt_i32 s3, 0
	s_cselect_b32 s23, 49, 48
	s_mul_i32 s3, s3, s23
	s_add_i32 s3, s3, s22
	s_mul_hi_i32 s22, s3, 0x2aaaaaab
	s_lshr_b32 s23, s22, 31
	s_ashr_i32 s22, s22, 3
	s_add_i32 s22, s22, s23
	s_lshl_b32 s23, s22, 3
	s_mul_i32 s22, s22, 48
	s_sub_i32 s3, s3, s22
	s_bfe_i32 s22, s3, 0x80000
	s_bfe_u32 s22, s22, 0x3000c
	s_add_i32 s22, s3, s22
	s_bfe_i32 s24, s22, 0x80000
	s_and_b32 s22, s22, 0xf8
	s_sub_i32 s3, s3, s22
	s_sext_i32_i16 s24, s24
	s_sext_i32_i8 s3, s3
	s_add_i32 s22, s23, s3
	s_ashr_i32 s64, s24, 3

; #define LAS __attribute__((address_space(3)))
; __device__ __forceinline__ int opaque_tid() { int t = threadIdx.x; asm volatile("" : "+v"(t)); return t; }
; __device__ __forceinline__ void gla_intra_unit(const Params& P, LAS unsigned char* lds, int unit) {
;     const int tid = opaque_tid(), lane = tid & 63, wid = tid >> 6, fr = lane & 15, fq = lane >> 4;
;     const int bh = unit >> 7, n = unit & 127, b = bh >> 2, h = bh & 3;
;     const size_t t0 = (size_t)b * SEQ + 64 * n;
;     const bf16_t* Z = (const bf16_t*)P.out;
;     LAS float* ag = (LAS float*)(lds + G1_AG); LAS float* seg = (LAS float*)(lds + G1_SEG);
;     LAS bf16_t* qd = (LAS bf16_t*)(lds + G1_QD); LAS bf16_t* ki = (LAS bf16_t*)(lds + G1_KI); LAS bf16_t* kdT = (LAS bf16_t*)(lds + G1_KDT);
;     LAS bf16_t* vT = (LAS bf16_t*)(lds + G1_VT); LAS bf16_t* at = (LAS bf16_t*)(lds + G1_AT);
;     bf16_t* qdec_g = (bf16_t*)(P.ws + WS_QDEC); float* decay_g = (float*)(P.ws + WS_DECAY); bf16_t* OI = (bf16_t*)(P.ws + WS_OI); bf16_t* DS = (bf16_t*)(P.ws + WS_XN);
;     const int d_ = tid & 127, cgp_ = tid >> 7;
;     float wg_[16];
; #pragma unroll
;     for (int r = 0; r < 16; ++r) wg_[r] = P.w_gate_up[r * 512 + 128 * h + d_];
;     const float bias_ = P.b_gate[128 * h + d_];
; __global__ void __launch_bounds__(NTHREADS, 2) hybrid_block_fwd(Params P) {
;     ...
;     if (PH(7)) for (int rep = 0; rep < REP_GLA; ++rep) for (int u = bx; u < 1024; u += G) gla_intra_unit(P, lds, u);
.LBB0_421:
	v_readlane_b32 s0, v240, 10
	v_readlane_b32 s1, v240, 11
	s_add_u32 s28, s58, 0x12800000
	s_addc_u32 s29, s59, 0
	v_cndmask_b32_e64 v0, 0, 1, s[0:1]
	v_cmp_ne_u32_e64 s[76:77], 1, v0
	s_andn2_b64 vcc, exec, s[0:1]
	s_cbranch_vccnz .LBB0_430
	s_cmp_eq_u32 s98, 2
	s_cbranch_scc1 .LBB0_430
	s_ashr_i32 s3, s2, 31
	s_lshl_b32 s22, s2, 6
	s_lshl_b32 s23, s92, 6
	s_lshl_b64 s[0:1], s[2:3], 9
	s_add_u32 s0, s58, s0
	s_addc_u32 s1, s59, s1
	s_add_u32 s36, s0, 0x200000
	s_addc_u32 s37, s1, 0
	s_ashr_i32 s93, s92, 31
	s_lshl_b64 s[40:41], s[92:93], 9
	s_lshl_b64 s[52:53], s[2:3], 8
	s_lshl_b64 s[54:55], s[92:93], 8
	s_lshl_b64 s[0:1], s[2:3], 14
	s_add_u32 s0, s58, s0
	s_addc_u32 s1, s59, s1
	s_add_u32 s68, s0, 0x11800000
	s_addc_u32 s69, s1, 0
	s_lshl_b64 s[70:71], s[92:93], 14
	s_mov_b32 s39, 0
	v_mov_b32_e32 v105, 0
	s_movk_i32 s3, 0x1000
	s_movk_i32 s26, 0x2000
	s_movk_i32 s27, 0x4000
	s_movk_i32 s33, 0x6000
	s_movk_i32 s43, 0x90
	s_mov_b32 s44, 0xbfb8aa3b
	s_mov_b32 s45, 0x800000
	s_mov_b32 s50, 0x3f317217
	s_mov_b32 s51, 0x7f800000
	v_mov_b32_e32 v118, 0x41b17218
	s_movk_i32 s62, 0x7fff
	s_movk_i32 s63, 0x110
	v_mov_b32_e32 v119, 0x900
	v_mov_b32_e32 v120, 0x1200
	v_mov_b32_e32 v121, 0x1b00
	v_readlane_b32 s66, v241, 14
	s_branch .LBB0_424

; __global__ void __launch_bounds__(NTHREADS, 2) hybrid_block_fwd(Params P) {
;     ...
;       pg8::EpiRowScaleRope E{(bf16_t*)(ws + WS_Q), QC, QSCALE, 4, (const float*)(ws + WS_CS)};
;     ...
;     if (PH(7)) for (int rep = 0; rep < REP_GLA; ++rep) for (int u = bx; u < 1024; u += G) gla_intra_unit(P, lds, u);
.Lp3_gla_done:
	s_cmp_eq_u32 s98, 1
	s_cbranch_scc0 .LBB0_430
	s_mov_b32 s98, 2
	s_mov_b64 s[28:29], s[100:101]
	s_add_u32 s54, s58, 0x300000
	s_addc_u32 s55, s59, 0
	v_mov_b32_e32 v12, v168
	s_cmpk_lt_i32 s2, 0x180
	s_branch .Lp3_gemm_entry

; __global__ void __launch_bounds__(NTHREADS, 2) hybrid_block_fwd(Params P) {
	.amdhsa_kernel _Z16hybrid_block_fwd6Params
		.amdhsa_group_segment_fixed_size 0
		.amdhsa_private_segment_fixed_size 0
		.amdhsa_kernarg_size 448
		.amdhsa_user_sgpr_count 2
		.amdhsa_user_sgpr_dispatch_ptr 0
		.amdhsa_user_sgpr_queue_ptr 0
		.amdhsa_user_sgpr_kernarg_segment_ptr 1
		.amdhsa_user_sgpr_dispatch_id 0
		.amdhsa_user_sgpr_kernarg_preload_length 0
		.amdhsa_user_sgpr_kernarg_preload_offset 0
		.amdhsa_user_sgpr_private_segment_size 0
		.amdhsa_uses_dynamic_stack 0
		.amdhsa_enable_private_segment 0
		.amdhsa_system_sgpr_workgroup_id_x 1
		.amdhsa_system_sgpr_workgroup_id_y 0
		.amdhsa_system_sgpr_workgroup_id_z 0
		.amdhsa_system_sgpr_workgroup_info 0
		.amdhsa_system_vgpr_workitem_id 2
		.amdhsa_next_free_vgpr 256
		.amdhsa_next_free_sgpr 102
		.amdhsa_accum_offset 256
		.amdhsa_reserve_vcc 1
		.amdhsa_float_round_mode_32 0
		.amdhsa_float_round_mode_16_64 0
		.amdhsa_float_denorm_mode_32 3
		.amdhsa_float_denorm_mode_16_64 3
		.amdhsa_dx10_clamp 1
		.amdhsa_ieee_mode 1
		.amdhsa_fp16_overflow 0
		.amdhsa_tg_split 0
		.amdhsa_exception_fp_ieee_invalid_op 0
		.amdhsa_exception_fp_denorm_src 0
		.amdhsa_exception_fp_ieee_div_zero 0
		.amdhsa_exception_fp_ieee_overflow 0
		.amdhsa_exception_fp_ieee_underflow 0
		.amdhsa_exception_fp_ieee_inexact 0
		.amdhsa_exception_int_div_zero 0
	.end_amdhsa_kernel

; __global__ void __launch_bounds__(NTHREADS, 2) hybrid_block_fwd(Params P) {
.Lfunc_end0:
	.size	_Z16hybrid_block_fwd6Params, .Lfunc_end0-_Z16hybrid_block_fwd6Params
	.set _Z16hybrid_block_fwd6Params.num_vgpr, 256
	.set _Z16hybrid_block_fwd6Params.num_agpr, 0
	.set _Z16hybrid_block_fwd6Params.numbered_sgpr, 102
	.set _Z16hybrid_block_fwd6Params.num_named_barrier, 0
	.set _Z16hybrid_block_fwd6Params.private_seg_size, 0
	.set _Z16hybrid_block_fwd6Params.uses_vcc, 1
	.set _Z16hybrid_block_fwd6Params.uses_flat_scratch, 0
	.set _Z16hybrid_block_fwd6Params.has_dyn_sized_stack, 0
	.set _Z16hybrid_block_fwd6Params.has_recursion, 0
	.set _Z16hybrid_block_fwd6Params.has_indirect_call, 0

; __global__ void __launch_bounds__(NTHREADS, 2) hybrid_block_fwd(Params P) {
amdhsa.kernels:
  - .agpr_count:     0
    .args:
      - .offset:         0
        .size:           192
        .value_kind:     by_value
      - .offset:         192
        .size:           4
        .value_kind:     hidden_block_count_x
      - .offset:         196
        .size:           4
        .value_kind:     hidden_block_count_y
      - .offset:         200
        .size:           4
        .value_kind:     hidden_block_count_z
      - .offset:         204
        .size:           2
        .value_kind:     hidden_group_size_x
      - .offset:         206
        .size:           2
        .value_kind:     hidden_group_size_y
      - .offset:         208
        .size:           2
        .value_kind:     hidden_group_size_z
      - .offset:         210
        .size:           2
        .value_kind:     hidden_remainder_x
      - .offset:         212
        .size:           2
        .value_kind:     hidden_remainder_y
      - .offset:         214
        .size:           2
        .value_kind:     hidden_remainder_z
      - .offset:         232
        .size:           8
        .value_kind:     hidden_global_offset_x
      - .offset:         240
        .size:           8
        .value_kind:     hidden_global_offset_y
      - .offset:         248
        .size:           8
        .value_kind:     hidden_global_offset_z
      - .offset:         256
        .size:           2
        .value_kind:     hidden_grid_dims
      - .offset:         280
        .size:           8
        .value_kind:     hidden_multigrid_sync_arg
      - .offset:         312
        .size:           4
        .value_kind:     hidden_dynamic_lds_size
    .group_segment_fixed_size: 0
    .kernarg_segment_align: 8
    .kernarg_segment_size: 448
    .language:       OpenCL C
    .language_version:
      - 2
      - 0
    .max_flat_workgroup_size: 512
    .name:           _Z16hybrid_block_fwd6Params
    .private_segment_fixed_size: 0
    .sgpr_count:     108
    .sgpr_spill_count: 81
    .symbol:         _Z16hybrid_block_fwd6Params.kd
    .uniform_work_group_size: 1
    .uses_dynamic_stack: false
    .vgpr_count:     256
    .vgpr_spill_count: 0
    .wavefront_size: 64
